# FFN2 gate-up tail row-pass chunks: gain vectors hoisted into registers, per-load and pre-load full waits removed
# baseline (speedup 1.0000x reference)
; template <int MODE>
; __device__ __forceinline__ void row_load(const Params& p, int r, int lane, const bf16_t* Dsrc, f32x4 (&h)[8], u32x2 (&dw)[8]) {
;     if (r >= ROWS || (MODE >= 2 && r >= NTOKR)) return;
;     const f32x4* hs = (const f32x4*)((MODE <= 1) ? h0row(p, r) : (const float*)hrow(p, r));
; #pragma unroll
;     for (int j = 0; j < 8; ++j) h[j] = __builtin_nontemporal_load(&hs[lane + 64 * j]);
;     if (MODE >= 1) { const u32x2* dp = (const u32x2*)(Dsrc + (size_t)r * DM);
; #pragma unroll
;         for (int j = 0; j < 8; ++j) dw[j] = __builtin_nontemporal_load(&dp[lane + 64 * j]); }
; }
; template <int MODE>
; __device__ __forceinline__ void row_finish(const Params& p, int r, int lane, const float* gpost, const float* gnext, bf16_t* U, float coef, f32x4 (&h)[8], const u32x2 (&dw)[8]) {
;     if (r >= ROWSP) return;
;     if (r >= ROWS) { if (MODE != 3) { u32x4* up = (u32x4*)(U + (size_t)r * DM);
; #pragma unroll
;             for (int j = 0; j < 4; ++j) up[lane + 64 * j] = (u32x4){0u, 0u, 0u, 0u}; } return; }
;     if (MODE >= 2 && r >= NTOKR) return;
;     if (MODE >= 1) {
;         f32x4 d[8]; float ss = 0.f;
; #pragma unroll
;         for (int j = 0; j < 8; ++j) { const u32x2 w = dw[j]; d[j] = (f32x4){bflo(w.x), bfhi(w.x), bflo(w.y), bfhi(w.y)};
;             ss += (d[j].x * d[j].x + d[j].y * d[j].y) + (d[j].z * d[j].z + d[j].w * d[j].w); }
;         ss = wave_sum(ss);
;         const float rs = rsqrtf(ss * (1.f / DM) + EPS) * coef;
;         f32x4* hd = (f32x4*)hrow(p, r);
; #pragma unroll
;     for (int n = 0; n < max_chunks; ++n) {
;         if (tid == 0) MISC[0] = (int)atomicAdd(ctr, 1u);
;         __syncthreads();
;         const int c = __builtin_amdgcn_readfirstlane(MISC[0]);
;         __syncthreads();
;         if (c >= RP_CHUNKS) break;
;         const int r0 = (chunk0 + c) * 64 + wave * 8;
; #pragma unroll 1
;         for (int k = 0; k < 8; k += 2) {
;             f32x4 ha[8], hb[8]; u32x2 da[8], db[8];
;             row_load<MODE>(p, r0 + k, lane, Dsrc, ha, da);
;             row_load<MODE>(p, r0 + k + 1, lane, Dsrc, hb, db);
;             row_finish<MODE>(p, r0 + k, lane, gpost, gnext, U, coef, ha, da);
;             row_finish<MODE>(p, r0 + k + 1, lane, gpost, gnext, U, coef, hb, db);
;         }
;     }
; }
.LBB0_1713:
	s_andn2_b64 vcc, exec, s[34:35]
	v_cmp_eq_u32_e64 s[38:39], 0, v160
	s_cbranch_vccnz .LBB0_1730
	s_waitcnt vmcnt(0)
	v_and_b32_e32 v2, 63, v160
	v_lshlrev_b32_e32 v128, 4, v2
	v_or_b32_e32 v0, 0x1000, v128
	v_mov_b32_e32 v1, v129
	v_lshl_add_u64 v[66:67], s[12:13], 0, v[0:1]
	v_or_b32_e32 v0, 0x1400, v128
	v_lshl_add_u64 v[68:69], s[12:13], 0, v[0:1]
	v_or_b32_e32 v0, 0x1800, v128
	v_lshl_add_u64 v[70:71], s[12:13], 0, v[0:1]
	v_or_b32_e32 v0, 0x1c00, v128
	v_lshl_add_u64 v[72:73], s[12:13], 0, v[0:1]
	v_and_b32_e32 v0, 64, v224
	v_add_u32_e32 v0, 64, v0
	v_xor_b32_e32 v1, 1, v224
	v_cmp_lt_i32_e32 vcc, v1, v0
	s_add_u32 s40, s40, 0x9d8001c
	s_addc_u32 s41, s41, 0
	v_cndmask_b32_e32 v1, v224, v1, vcc
	v_lshlrev_b32_e32 v161, 2, v1
	v_xor_b32_e32 v1, 2, v224
	v_cmp_lt_i32_e32 vcc, v1, v0
	s_lshl_b32 s54, s75, 3
	v_lshl_add_u64 v[64:65], s[12:13], 0, v[128:129]
	v_cndmask_b32_e32 v1, v224, v1, vcc
	v_lshlrev_b32_e32 v162, 2, v1
	v_xor_b32_e32 v1, 4, v224
	v_cmp_lt_i32_e32 vcc, v1, v0
	v_lshl_add_u64 v[76:77], s[14:15], 0, v[128:129]
	s_nop 0
	v_cndmask_b32_e32 v1, v224, v1, vcc
	v_lshlrev_b32_e32 v163, 2, v1
	v_xor_b32_e32 v1, 8, v224
	v_cmp_lt_i32_e32 vcc, v1, v0
	s_nop 1
	v_cndmask_b32_e32 v1, v224, v1, vcc
	v_lshlrev_b32_e32 v164, 2, v1
	v_xor_b32_e32 v1, 16, v224
	v_cmp_lt_i32_e32 vcc, v1, v0
	s_nop 1
	v_cndmask_b32_e32 v1, v224, v1, vcc
	v_lshlrev_b32_e32 v165, 2, v1
	v_xor_b32_e32 v1, 32, v224
	v_cmp_lt_i32_e32 vcc, v1, v0
	s_nop 1
	v_cndmask_b32_e32 v0, v224, v1, vcc
	v_lshlrev_b32_e32 v166, 2, v0
	v_lshlrev_b32_e32 v0, 3, v2
	v_mov_b32_e32 v1, v129
	v_lshl_add_u64 v[74:75], s[28:29], 0, v[0:1]
	v_mov_b32_e32 v0, 0
	s_mov_b64 s[28:29], 0
	v_mov_b32_e32 v1, v0
	v_mov_b32_e32 v2, v0
	v_mov_b32_e32 v3, v0
	v_mov_b32_e32 v20, v0
	v_mov_b32_e32 v21, v0
	v_mov_b32_e32 v22, v0
	v_mov_b32_e32 v23, v0
	v_mov_b32_e32 v24, v0
	v_mov_b32_e32 v25, v0
	v_mov_b32_e32 v26, v0
	v_mov_b32_e32 v27, v0
	v_mov_b32_e32 v32, v0
	v_mov_b32_e32 v33, v0
	v_mov_b32_e32 v34, v0
	v_mov_b32_e32 v35, v0
	v_mov_b32_e32 v48, v0
	v_mov_b32_e32 v49, v0
	v_mov_b32_e32 v50, v0
	v_mov_b32_e32 v51, v0
	v_mov_b32_e32 v52, v0
	v_mov_b32_e32 v53, v0
	v_mov_b32_e32 v54, v0
	v_mov_b32_e32 v55, v0
	v_mov_b32_e32 v56, v0
	v_mov_b32_e32 v57, v0
	v_mov_b32_e32 v58, v0
	v_mov_b32_e32 v59, v0
	v_mov_b32_e32 v60, v0
	v_mov_b32_e32 v61, v0
	v_mov_b32_e32 v62, v0
	v_mov_b32_e32 v63, v0
	global_load_dwordx4 v[180:183], v[64:65], off
	global_load_dwordx4 v[184:187], v[64:65], off offset:1024
	global_load_dwordx4 v[188:191], v[64:65], off offset:2048
	global_load_dwordx4 v[192:195], v[64:65], off offset:3072
	global_load_dwordx4 v[196:199], v[66:67], off
	global_load_dwordx4 v[200:203], v[68:69], off
	global_load_dwordx4 v[204:207], v[70:71], off
	global_load_dwordx4 v[208:211], v[72:73], off
	s_waitcnt vmcnt(0)
	s_branch .LBB0_1717

; template <int MODE>
; __device__ __forceinline__ void row_load(const Params& p, int r, int lane, const bf16_t* Dsrc, f32x4 (&h)[8], u32x2 (&dw)[8]) {
;     if (r >= ROWS || (MODE >= 2 && r >= NTOKR)) return;
;     const f32x4* hs = (const f32x4*)((MODE <= 1) ? h0row(p, r) : (const float*)hrow(p, r));
; #pragma unroll
;     for (int j = 0; j < 8; ++j) h[j] = __builtin_nontemporal_load(&hs[lane + 64 * j]);
;     if (MODE >= 1) { const u32x2* dp = (const u32x2*)(Dsrc + (size_t)r * DM);
; #pragma unroll
;         for (int j = 0; j < 8; ++j) dw[j] = __builtin_nontemporal_load(&dp[lane + 64 * j]); }
; }
; template <int MODE>
; __device__ __forceinline__ void row_finish(const Params& p, int r, int lane, const float* gpost, const float* gnext, bf16_t* U, float coef, f32x4 (&h)[8], const u32x2 (&dw)[8]) {
;     ...
;     if (MODE >= 1) {
;         f32x4 d[8]; float ss = 0.f;
; #pragma unroll
;         for (int j = 0; j < 8; ++j) { const u32x2 w = dw[j]; d[j] = (f32x4){bflo(w.x), bfhi(w.x), bflo(w.y), bfhi(w.y)};
;             ss += (d[j].x * d[j].x + d[j].y * d[j].y) + (d[j].z * d[j].z + d[j].w * d[j].w); }
;         ss = wave_sum(ss);
;         const float rs = rsqrtf(ss * (1.f / DM) + EPS) * coef;
.LBB0_1726:
	v_add_co_u32_e32 v60, vcc, 0x1000, v112
	global_load_dwordx4 v[0:3], v[112:113], off nt
	global_load_dwordx4 v[20:23], v[112:113], off offset:1024 nt
	global_load_dwordx4 v[24:27], v[112:113], off offset:2048 nt
	global_load_dwordx4 v[32:35], v[112:113], off offset:3072 nt
	v_addc_co_u32_e32 v61, vcc, 0, v113, vcc
	global_load_dwordx4 v[48:51], v[60:61], off nt
	global_load_dwordx4 v[52:55], v[60:61], off offset:1024 nt
	global_load_dwordx4 v[56:59], v[60:61], off offset:2048 nt
	s_nop 0
	global_load_dwordx4 v[60:63], v[60:61], off offset:3072 nt
	s_waitcnt lgkmcnt(0)
	flat_load_dwordx2 v[94:95], v[110:111] nt
	flat_load_dwordx2 v[96:97], v[110:111] offset:512 nt
	flat_load_dwordx2 v[98:99], v[110:111] offset:1024 nt
	flat_load_dwordx2 v[100:101], v[110:111] offset:1536 nt
	flat_load_dwordx2 v[102:103], v[110:111] offset:2048 nt
	flat_load_dwordx2 v[104:105], v[110:111] offset:2560 nt
	flat_load_dwordx2 v[106:107], v[110:111] offset:3072 nt
	flat_load_dwordx2 v[108:109], v[110:111] offset:3584 nt
	s_cmpk_lt_i32 s55, 0x7fff
	s_cselect_b64 s[50:51], -1, 0
	s_cmpk_gt_i32 s55, 0x7ffe
	s_cbranch_scc1 .LBB0_1724
.LBB0_1727:
	v_add_co_u32_e32 v16, vcc, 0x2000, v112
	s_nop 1
	v_addc_co_u32_e32 v17, vcc, 0, v113, vcc
	v_add_co_u32_e32 v44, vcc, 0x3000, v112
	global_load_dwordx4 v[4:7], v[16:17], off nt
	global_load_dwordx4 v[8:11], v[16:17], off offset:1024 nt
	global_load_dwordx4 v[12:15], v[16:17], off offset:2048 nt
	s_nop 0
	global_load_dwordx4 v[16:19], v[16:17], off offset:3072 nt
	v_addc_co_u32_e32 v45, vcc, 0, v113, vcc
	s_waitcnt lgkmcnt(0)
	v_add_co_u32_e32 v92, vcc, 0x1000, v110
	global_load_dwordx4 v[28:31], v[44:45], off nt
	global_load_dwordx4 v[36:39], v[44:45], off offset:1024 nt
	global_load_dwordx4 v[40:43], v[44:45], off offset:2048 nt
	s_nop 0
	global_load_dwordx4 v[44:47], v[44:45], off offset:3072 nt
	v_addc_co_u32_e32 v93, vcc, 0, v111, vcc
	flat_load_dwordx2 v[78:79], v[92:93] nt
	flat_load_dwordx2 v[80:81], v[92:93] offset:512 nt
	flat_load_dwordx2 v[82:83], v[92:93] offset:1024 nt
	flat_load_dwordx2 v[84:85], v[92:93] offset:1536 nt
	flat_load_dwordx2 v[86:87], v[92:93] offset:2048 nt
	flat_load_dwordx2 v[88:89], v[92:93] offset:2560 nt
	flat_load_dwordx2 v[90:91], v[92:93] offset:3072 nt
	s_nop 0
	flat_load_dwordx2 v[92:93], v[92:93] offset:3584 nt
	s_andn2_b64 vcc, exec, s[52:53]
	s_cbranch_vccnz .LBB0_1725
.LBB0_1728:
	s_waitcnt vmcnt(0) lgkmcnt(0)
	v_and_b32_e32 v155, 0xffff0000, v94
	v_and_b32_e32 v154, 0xffff0000, v96
	v_and_b32_e32 v157, 0xffff0000, v95
	v_and_b32_e32 v156, 0xffff0000, v97
	v_lshlrev_b32_e32 v153, 16, v94
	v_lshlrev_b32_e32 v152, 16, v96
	v_lshlrev_b32_e32 v151, 16, v95
	v_lshlrev_b32_e32 v150, 16, v97
	v_pk_mul_f32 v[114:115], v[154:155], v[154:155]
	v_pk_mul_f32 v[116:117], v[156:157], v[156:157]
	v_pk_fma_f32 v[114:115], v[152:153], v[152:153], v[114:115]
	v_pk_fma_f32 v[116:117], v[150:151], v[150:151], v[116:117]
	v_and_b32_e32 v147, 0xffff0000, v99
	v_pk_add_f32 v[114:115], v[114:115], v[116:117]
	v_and_b32_e32 v146, 0xffff0000, v98
	v_pk_add_f32 v[114:115], v[114:115], v[114:115] op_sel_hi:[0,1]
	v_lshlrev_b32_e32 v149, 16, v99
	v_lshlrev_b32_e32 v148, 16, v98
	v_pk_mul_f32 v[116:117], v[146:147], v[146:147]
	v_lshlrev_b32_e32 v142, 16, v100
	v_and_b32_e32 v143, 0xffff0000, v100
	v_lshlrev_b32_e32 v144, 16, v101
	v_lshlrev_b32_e32 v138, 16, v102
	v_pk_fma_f32 v[116:117], v[148:149], v[148:149], v[116:117]
	v_mul_f32_e32 v139, v142, v142
	v_mul_f32_e32 v119, v143, v143
	v_and_b32_e32 v145, 0xffff0000, v101
	v_mul_f32_e32 v114, v144, v144
	v_mov_b32_e32 v118, v138
	v_pk_add_f32 v[116:117], v[116:117], v[116:117] op_sel_hi:[0,1]
	v_pk_fma_f32 v[120:121], v[144:145], v[144:145], v[114:115] op_sel_hi:[1,1,0]
	v_and_b32_e32 v128, 0xffff0000, v102
	v_lshlrev_b32_e32 v140, 16, v103
	v_and_b32_e32 v141, 0xffff0000, v103
	v_pk_add_f32 v[118:119], v[138:139], v[118:119]
	v_mul_f32_e32 v120, v128, v128
	v_mul_f32_e32 v116, v140, v140
	v_mul_f32_e32 v114, v141, v141
	v_mul_f32_e32 v122, v138, v138
	v_mov_b32_e32 v123, v119
	v_pk_add_f32 v[118:119], v[122:123], v[120:121]
	v_pk_add_f32 v[114:115], v[116:117], v[114:115]
	v_and_b32_e32 v125, 0xffff0000, v105
	v_pk_add_f32 v[114:115], v[118:119], v[114:115]
	v_and_b32_e32 v124, 0xffff0000, v104
	v_pk_add_f32 v[168:169], v[114:115], v[114:115] op_sel_hi:[0,1]
	v_lshlrev_b32_e32 v127, 16, v105
	v_lshlrev_b32_e32 v126, 16, v104
	v_pk_mul_f32 v[114:115], v[124:125], v[124:125]
	v_lshlrev_b32_e32 v118, 16, v106
	v_pk_fma_f32 v[114:115], v[126:127], v[126:127], v[114:115]
	v_lshlrev_b32_e32 v120, 16, v107
	v_pk_add_f32 v[170:171], v[114:115], v[114:115] op_sel_hi:[0,1]
	v_mul_f32_e32 v115, v118, v118
	v_and_b32_e32 v121, 0xffff0000, v107
	v_mul_f32_e32 v114, v120, v120
	v_and_b32_e32 v119, 0xffff0000, v106
	v_pk_fma_f32 v[174:175], v[120:121], v[120:121], v[114:115] op_sel_hi:[1,1,0]
	v_lshlrev_b32_e32 v114, 16, v108
	v_mul_f32_e32 v173, v119, v119
	v_mov_b32_e32 v172, v114
	v_and_b32_e32 v123, 0xffff0000, v108
	v_lshlrev_b32_e32 v116, 16, v109
	v_and_b32_e32 v117, 0xffff0000, v109
	v_pk_add_f32 v[172:173], v[114:115], v[172:173]
	v_mul_f32_e32 v174, v123, v123
	v_mul_f32_e32 v170, v116, v116
	v_mul_f32_e32 v168, v117, v117
	v_mul_f32_e32 v176, v114, v114
	v_mov_b32_e32 v177, v173
	v_pk_add_f32 v[172:173], v[176:177], v[174:175]
	v_pk_add_f32 v[168:169], v[170:171], v[168:169]
	v_mov_b32_e32 v139, v128
	v_pk_add_f32 v[168:169], v[172:173], v[168:169]
	v_mov_b32_e32 v172, v153
	v_add_f32_e32 v115, v168, v169
	v_mov_b64_e32 v[168:169], v[180:181]
	v_mov_b64_e32 v[170:171], v[182:183]
	ds_bpermute_b32 v122, v161, v115
	v_mov_b32_e32 v173, v155
	v_mov_b32_e32 v153, v154
	v_mov_b32_e32 v154, v148
	v_mov_b32_e32 v155, v146
	s_waitcnt lgkmcnt(0)
; template <int MODE>
; __device__ __forceinline__ void row_finish(const Params& p, int r, int lane, const float* gpost, const float* gnext, bf16_t* U, float coef, f32x4 (&h)[8], const u32x2 (&dw)[8]) {
;     ...
;         for (int j = 0; j < 8; ++j) { const u32x2 w = dw[j]; d[j] = (f32x4){bflo(w.x), bfhi(w.x), bflo(w.y), bfhi(w.y)};
;             ss += (d[j].x * d[j].x + d[j].y * d[j].y) + (d[j].z * d[j].z + d[j].w * d[j].w); }
;         ss = wave_sum(ss);
;         const float rs = rsqrtf(ss * (1.f / DM) + EPS) * coef;
;         f32x4* hd = (f32x4*)hrow(p, r);
; #pragma unroll
;         for (int j = 0; j < 8; ++j) { const f32x4 g = ((const f32x4*)gpost)[lane + 64 * j]; h[j] = h[j] + d[j] * g * rs; __builtin_nontemporal_store(h[j], &hd[lane + 64 * j]); }
;     }
	v_add_f32_e32 v115, v115, v122
	ds_bpermute_b32 v122, v162, v115
	v_mov_b32_e32 v146, v149
	s_waitcnt lgkmcnt(0)
	v_add_f32_e32 v115, v115, v122
	ds_bpermute_b32 v122, v163, v115
	s_waitcnt lgkmcnt(0)
	v_add_f32_e32 v115, v115, v122
	ds_bpermute_b32 v122, v164, v115
	s_waitcnt lgkmcnt(0)
	v_add_f32_e32 v115, v115, v122
	ds_bpermute_b32 v122, v165, v115
	s_waitcnt lgkmcnt(0)
	v_add_f32_e32 v115, v115, v122
	ds_bpermute_b32 v122, v166, v115
	s_waitcnt lgkmcnt(0)
	v_add_f32_e32 v115, v115, v122
	v_fmamk_f32 v115, v115, 0x3a000000, v159
	v_cmp_gt_f32_e32 vcc, s70, v115
	v_mul_f32_e32 v122, 0x4b800000, v115
	v_pk_mul_f32 v[168:169], v[172:173], v[168:169]
	v_cndmask_b32_e32 v115, v115, v122, vcc
	v_rsq_f32_e32 v115, v115
	v_mov_b32_e32 v172, v151
	v_mov_b32_e32 v173, v157
	v_pk_mul_f32 v[170:171], v[172:173], v[170:171]
	v_mul_f32_e32 v122, 0x45800000, v115
	v_cndmask_b32_e32 v115, v115, v122, vcc
	v_mul_f32_e32 v122, 0.5, v115
	v_pk_fma_f32 v[2:3], v[170:171], v[122:123], v[2:3] op_sel_hi:[1,0,1]
	v_pk_fma_f32 v[0:1], v[168:169], v[122:123], v[0:1] op_sel_hi:[1,0,1]
	global_store_dwordx4 v[112:113], v[0:3], off nt
	v_mov_b64_e32 v[168:169], v[184:185]
	v_mov_b64_e32 v[170:171], v[186:187]
	v_mov_b32_e32 v151, v156
	v_mov_b32_e32 v115, v123
	v_pk_mul_f32 v[152:153], v[152:153], v[168:169]
	v_pk_mul_f32 v[150:151], v[150:151], v[170:171]
	v_pk_fma_f32 v[20:21], v[152:153], v[122:123], v[20:21] op_sel_hi:[1,0,1]
	v_pk_fma_f32 v[22:23], v[150:151], v[122:123], v[22:23] op_sel_hi:[1,0,1]
	global_store_dwordx4 v[112:113], v[20:23], off offset:1024 nt
	v_mov_b64_e32 v[150:151], v[188:189]
	v_mov_b64_e32 v[152:153], v[190:191]
	v_pk_mul_f32 v[150:151], v[150:151], v[154:155]
	v_pk_mul_f32 v[146:147], v[152:153], v[146:147]
	v_pk_fma_f32 v[24:25], v[150:151], v[122:123], v[24:25] op_sel_hi:[1,0,1]
	v_pk_fma_f32 v[26:27], v[146:147], v[122:123], v[26:27] op_sel_hi:[1,0,1]
	global_store_dwordx4 v[112:113], v[24:27], off offset:2048 nt
	v_mov_b64_e32 v[146:147], v[192:193]
	v_mov_b64_e32 v[148:149], v[194:195]
	v_pk_mul_f32 v[142:143], v[142:143], v[146:147]
	v_pk_mul_f32 v[144:145], v[144:145], v[148:149]
	v_pk_fma_f32 v[32:33], v[142:143], v[122:123], v[32:33] op_sel_hi:[1,0,1]
	v_pk_fma_f32 v[34:35], v[144:145], v[122:123], v[34:35] op_sel_hi:[1,0,1]
	global_store_dwordx4 v[112:113], v[32:35], off offset:3072 nt
	v_mov_b64_e32 v[142:143], v[196:197]
	v_mov_b64_e32 v[144:145], v[198:199]
	v_pk_mul_f32 v[138:139], v[138:139], v[142:143]
	v_pk_mul_f32 v[140:141], v[140:141], v[144:145]
	v_add_co_u32_e32 v142, vcc, s31, v112
	v_pk_fma_f32 v[50:51], v[140:141], v[122:123], v[50:51] op_sel_hi:[1,0,1]
	v_pk_fma_f32 v[48:49], v[138:139], v[122:123], v[48:49] op_sel_hi:[1,0,1]
	v_addc_co_u32_e32 v143, vcc, 0, v113, vcc
	global_store_dwordx4 v[142:143], v[48:51], off nt
	v_mov_b64_e32 v[138:139], v[200:201]
	v_mov_b64_e32 v[140:141], v[202:203]
	v_mov_b32_e32 v144, v126
	v_mov_b32_e32 v145, v124
	v_mov_b32_e32 v124, v127
	v_pk_mul_f32 v[138:139], v[138:139], v[144:145]
	v_pk_mul_f32 v[124:125], v[140:141], v[124:125]
	v_pk_fma_f32 v[52:53], v[122:123], v[138:139], v[52:53] op_sel_hi:[0,1,1]
	v_pk_fma_f32 v[54:55], v[122:123], v[124:125], v[54:55] op_sel_hi:[0,1,1]
	global_store_dwordx4 v[142:143], v[52:55], off offset:1024 nt
	v_mov_b64_e32 v[124:125], v[204:205]
	v_mov_b64_e32 v[126:127], v[206:207]
	v_pk_mul_f32 v[118:119], v[118:119], v[124:125]
	v_pk_mul_f32 v[120:121], v[120:121], v[126:127]
	v_pk_fma_f32 v[56:57], v[122:123], v[118:119], v[56:57] op_sel_hi:[0,1,1]
	v_pk_fma_f32 v[58:59], v[122:123], v[120:121], v[58:59] op_sel_hi:[0,1,1]
	global_store_dwordx4 v[142:143], v[56:59], off offset:2048 nt
	v_mov_b64_e32 v[118:119], v[208:209]
	v_mov_b64_e32 v[120:121], v[210:211]
	v_pk_mul_f32 v[114:115], v[114:115], v[118:119]
	v_pk_mul_f32 v[116:117], v[116:117], v[120:121]
	v_pk_fma_f32 v[60:61], v[122:123], v[114:115], v[60:61] op_sel_hi:[0,1,1]
	v_pk_fma_f32 v[62:63], v[122:123], v[116:117], v[62:63] op_sel_hi:[0,1,1]
	global_store_dwordx4 v[142:143], v[60:63], off offset:3072 nt
	s_andn2_b64 vcc, exec, s[50:51]
	s_cbranch_vccnz .LBB0_1721
.LBB0_1729:
	v_and_b32_e32 v153, 0xffff0000, v78
	v_and_b32_e32 v152, 0xffff0000, v80
	v_and_b32_e32 v157, 0xffff0000, v79
	v_and_b32_e32 v156, 0xffff0000, v81
	v_lshlrev_b32_e32 v149, 16, v78
	v_lshlrev_b32_e32 v148, 16, v80
	v_lshlrev_b32_e32 v155, 16, v79
	v_lshlrev_b32_e32 v154, 16, v81
	v_pk_mul_f32 v[114:115], v[152:153], v[152:153]
	v_pk_mul_f32 v[116:117], v[156:157], v[156:157]
	v_pk_fma_f32 v[114:115], v[148:149], v[148:149], v[114:115]
	v_pk_fma_f32 v[116:117], v[154:155], v[154:155], v[116:117]
	v_and_b32_e32 v151, 0xffff0000, v83
	v_pk_add_f32 v[114:115], v[114:115], v[116:117]
	v_and_b32_e32 v150, 0xffff0000, v82
	v_pk_add_f32 v[114:115], v[114:115], v[114:115] op_sel_hi:[0,1]
	v_lshlrev_b32_e32 v145, 16, v83
	v_lshlrev_b32_e32 v144, 16, v82
	v_pk_mul_f32 v[116:117], v[150:151], v[150:151]
	v_lshlrev_b32_e32 v140, 16, v84
	v_and_b32_e32 v141, 0xffff0000, v84
	v_lshlrev_b32_e32 v146, 16, v85
	v_lshlrev_b32_e32 v120, 16, v86
	v_pk_fma_f32 v[116:117], v[144:145], v[144:145], v[116:117]
	v_mul_f32_e32 v121, v140, v140
	v_mul_f32_e32 v119, v141, v141
	v_and_b32_e32 v147, 0xffff0000, v85
	v_mul_f32_e32 v114, v146, v146
	v_mov_b32_e32 v118, v120
	v_pk_add_f32 v[116:117], v[116:117], v[116:117] op_sel_hi:[0,1]
	v_pk_fma_f32 v[122:123], v[146:147], v[146:147], v[114:115] op_sel_hi:[1,1,0]
	v_and_b32_e32 v128, 0xffff0000, v86
	v_lshlrev_b32_e32 v142, 16, v87
	v_and_b32_e32 v143, 0xffff0000, v87
	v_pk_add_f32 v[118:119], v[120:121], v[118:119]
	v_mul_f32_e32 v122, v128, v128
	v_mul_f32_e32 v116, v142, v142
; template <int MODE>
; __device__ __forceinline__ void row_finish(const Params& p, int r, int lane, const float* gpost, const float* gnext, bf16_t* U, float coef, f32x4 (&h)[8], const u32x2 (&dw)[8]) {
;     ...
;         for (int j = 0; j < 8; ++j) { const u32x2 w = dw[j]; d[j] = (f32x4){bflo(w.x), bfhi(w.x), bflo(w.y), bfhi(w.y)};
;             ss += (d[j].x * d[j].x + d[j].y * d[j].y) + (d[j].z * d[j].z + d[j].w * d[j].w); }
;         ss = wave_sum(ss);
;         const float rs = rsqrtf(ss * (1.f / DM) + EPS) * coef;
;         f32x4* hd = (f32x4*)hrow(p, r);
; #pragma unroll
;         for (int j = 0; j < 8; ++j) { const f32x4 g = ((const f32x4*)gpost)[lane + 64 * j]; h[j] = h[j] + d[j] * g * rs; __builtin_nontemporal_store(h[j], &hd[lane + 64 * j]); }
;     }
	v_mul_f32_e32 v114, v143, v143
	v_mul_f32_e32 v124, v120, v120
	v_mov_b32_e32 v125, v119
	v_pk_add_f32 v[118:119], v[124:125], v[122:123]
	v_pk_add_f32 v[114:115], v[116:117], v[114:115]
	v_and_b32_e32 v139, 0xffff0000, v89
	v_pk_add_f32 v[114:115], v[118:119], v[114:115]
	v_and_b32_e32 v138, 0xffff0000, v88
	v_pk_add_f32 v[168:169], v[114:115], v[114:115] op_sel_hi:[0,1]
	v_lshlrev_b32_e32 v125, 16, v89
	v_lshlrev_b32_e32 v124, 16, v88
	v_pk_mul_f32 v[114:115], v[138:139], v[138:139]
	v_lshlrev_b32_e32 v118, 16, v90
	v_pk_fma_f32 v[114:115], v[124:125], v[124:125], v[114:115]
	v_lshlrev_b32_e32 v122, 16, v91
	v_pk_add_f32 v[170:171], v[114:115], v[114:115] op_sel_hi:[0,1]
	v_mul_f32_e32 v115, v118, v118
	v_and_b32_e32 v123, 0xffff0000, v91
	v_mul_f32_e32 v114, v122, v122
	v_and_b32_e32 v119, 0xffff0000, v90
	v_pk_fma_f32 v[174:175], v[122:123], v[122:123], v[114:115] op_sel_hi:[1,1,0]
	v_lshlrev_b32_e32 v114, 16, v92
	v_mul_f32_e32 v173, v119, v119
	v_mov_b32_e32 v172, v114
	v_and_b32_e32 v127, 0xffff0000, v92
	v_lshlrev_b32_e32 v116, 16, v93
	v_and_b32_e32 v117, 0xffff0000, v93
	v_pk_add_f32 v[172:173], v[114:115], v[172:173]
	v_mul_f32_e32 v174, v127, v127
	v_mul_f32_e32 v170, v116, v116
	v_mul_f32_e32 v168, v117, v117
	v_mul_f32_e32 v176, v114, v114
	v_mov_b32_e32 v177, v173
	v_pk_add_f32 v[172:173], v[176:177], v[174:175]
	v_pk_add_f32 v[168:169], v[170:171], v[168:169]
	s_nop 0
	v_pk_add_f32 v[168:169], v[172:173], v[168:169]
	v_mov_b32_e32 v172, v149
	v_add_f32_e32 v115, v168, v169
	v_mov_b64_e32 v[168:169], v[180:181]
	v_mov_b64_e32 v[170:171], v[182:183]
	ds_bpermute_b32 v121, v161, v115
	v_mov_b32_e32 v173, v153
	v_mov_b32_e32 v149, v152
	s_waitcnt lgkmcnt(0)
	v_add_f32_e32 v115, v115, v121
	ds_bpermute_b32 v121, v162, v115
	s_waitcnt lgkmcnt(0)
	v_add_f32_e32 v115, v115, v121
	ds_bpermute_b32 v121, v163, v115
	s_waitcnt lgkmcnt(0)
	v_add_f32_e32 v115, v115, v121
	ds_bpermute_b32 v121, v164, v115
	s_waitcnt lgkmcnt(0)
	v_add_f32_e32 v115, v115, v121
	ds_bpermute_b32 v121, v165, v115
	s_waitcnt lgkmcnt(0)
	v_add_f32_e32 v115, v115, v121
	ds_bpermute_b32 v121, v166, v115
	s_waitcnt lgkmcnt(0)
	v_add_f32_e32 v115, v115, v121
	v_fmamk_f32 v115, v115, 0x3a000000, v159
	v_cmp_gt_f32_e32 vcc, s70, v115
	v_mul_f32_e32 v121, 0x4b800000, v115
	v_pk_mul_f32 v[168:169], v[172:173], v[168:169]
	v_cndmask_b32_e32 v115, v115, v121, vcc
	v_rsq_f32_e32 v115, v115
	v_mov_b32_e32 v172, v155
	v_mov_b32_e32 v173, v157
	v_pk_mul_f32 v[170:171], v[172:173], v[170:171]
	v_mul_f32_e32 v121, 0x45800000, v115
	v_cndmask_b32_e32 v115, v115, v121, vcc
	v_add_co_u32_e32 v172, vcc, s1, v112
	v_mul_f32_e32 v126, 0.5, v115
	s_nop 0
	v_addc_co_u32_e32 v173, vcc, 0, v113, vcc
	v_add_co_u32_e32 v174, vcc, s69, v112
	v_pk_fma_f32 v[6:7], v[170:171], v[126:127], v[6:7] op_sel_hi:[1,0,1]
	v_pk_fma_f32 v[4:5], v[168:169], v[126:127], v[4:5] op_sel_hi:[1,0,1]
	v_addc_co_u32_e32 v175, vcc, 0, v113, vcc
	global_store_dwordx4 v[174:175], v[4:7], off offset:-4096 nt
	v_mov_b64_e32 v[168:169], v[184:185]
	v_mov_b64_e32 v[170:171], v[186:187]
	v_mov_b32_e32 v155, v156
	v_mov_b32_e32 v121, v128
	v_mov_b32_e32 v115, v127
	v_pk_mul_f32 v[154:155], v[154:155], v[170:171]
	v_pk_mul_f32 v[148:149], v[148:149], v[168:169]
	v_pk_fma_f32 v[10:11], v[154:155], v[126:127], v[10:11] op_sel_hi:[1,0,1]
	v_pk_fma_f32 v[8:9], v[148:149], v[126:127], v[8:9] op_sel_hi:[1,0,1]
	global_store_dwordx4 v[172:173], v[8:11], off offset:1024 nt
	v_mov_b64_e32 v[152:153], v[188:189]
	v_mov_b64_e32 v[154:155], v[190:191]
	v_mov_b32_e32 v148, v145
	v_mov_b32_e32 v149, v151
	v_mov_b32_e32 v145, v150
	v_pk_mul_f32 v[148:149], v[154:155], v[148:149]
	v_pk_mul_f32 v[144:145], v[152:153], v[144:145]
	v_pk_fma_f32 v[14:15], v[148:149], v[126:127], v[14:15] op_sel_hi:[1,0,1]
	v_pk_fma_f32 v[12:13], v[144:145], v[126:127], v[12:13] op_sel_hi:[1,0,1]
	global_store_dwordx4 v[172:173], v[12:15], off offset:2048 nt
	v_mov_b64_e32 v[148:149], v[192:193]
	v_mov_b64_e32 v[150:151], v[194:195]
	v_pk_mul_f32 v[144:145], v[146:147], v[150:151]
	v_pk_mul_f32 v[140:141], v[140:141], v[148:149]
	v_pk_fma_f32 v[18:19], v[144:145], v[126:127], v[18:19] op_sel_hi:[1,0,1]
	v_pk_fma_f32 v[16:17], v[140:141], v[126:127], v[16:17] op_sel_hi:[1,0,1]
	global_store_dwordx4 v[172:173], v[16:19], off offset:3072 nt
	v_mov_b64_e32 v[144:145], v[196:197]
	v_mov_b64_e32 v[146:147], v[198:199]
	v_pk_mul_f32 v[140:141], v[142:143], v[146:147]
	v_pk_mul_f32 v[120:121], v[120:121], v[144:145]
	v_pk_fma_f32 v[30:31], v[140:141], v[126:127], v[30:31] op_sel_hi:[1,0,1]
	v_pk_fma_f32 v[28:29], v[120:121], v[126:127], v[28:29] op_sel_hi:[1,0,1]
	global_store_dwordx4 v[174:175], v[28:31], off nt
	v_mov_b64_e32 v[140:141], v[200:201]
	v_mov_b64_e32 v[142:143], v[202:203]
	v_mov_b32_e32 v120, v125
	v_mov_b32_e32 v121, v139
	v_mov_b32_e32 v125, v138
	v_pk_mul_f32 v[120:121], v[142:143], v[120:121]
	v_pk_mul_f32 v[124:125], v[140:141], v[124:125]
	v_pk_fma_f32 v[38:39], v[126:127], v[120:121], v[38:39] op_sel_hi:[0,1,1]
	v_pk_fma_f32 v[36:37], v[126:127], v[124:125], v[36:37] op_sel_hi:[0,1,1]
	global_store_dwordx4 v[174:175], v[36:39], off offset:1024 nt
	v_mov_b64_e32 v[138:139], v[204:205]
	v_mov_b64_e32 v[140:141], v[206:207]
	v_pk_mul_f32 v[120:121], v[122:123], v[140:141]
	v_pk_mul_f32 v[118:119], v[118:119], v[138:139]
	v_pk_fma_f32 v[42:43], v[126:127], v[120:121], v[42:43] op_sel_hi:[0,1,1]
	v_pk_fma_f32 v[40:41], v[126:127], v[118:119], v[40:41] op_sel_hi:[0,1,1]
	global_store_dwordx4 v[174:175], v[40:43], off offset:2048 nt
	v_mov_b64_e32 v[118:119], v[208:209]
	v_mov_b64_e32 v[120:121], v[210:211]
	v_pk_mul_f32 v[116:117], v[116:117], v[120:121]
	v_pk_mul_f32 v[114:115], v[114:115], v[118:119]
	v_pk_fma_f32 v[46:47], v[126:127], v[116:117], v[46:47] op_sel_hi:[0,1,1]
	v_pk_fma_f32 v[44:45], v[126:127], v[114:115], v[44:45] op_sel_hi:[0,1,1]
	global_store_dwordx4 v[174:175], v[44:47], off offset:3072 nt
	s_branch .LBB0_1721
